# v6: accumulator zeroing with 64 v_mov_b64 instead of 128 v_mov_b32 in five GEMM phases, on top of v5
# speedup vs baseline: 1.0195x; 1.0195x over previous
; template <class Epi, class Sched, bool ALIGN_EPI, bool SP2>
; __device__ __forceinline__ void gemm_phase(LAS unsigned char* lds, const Gemm g, const Sched& S, const Epi& E) {
;     ...
;         const char* nA = has_next ? (const char*)(nxt.seg ? g.A1 : g.A0) + (size_t)nxt.pm * tstep : cA; const char* nB = has_next ? (const char*)(nxt.seg ? g.B1 : g.B0) + (size_t)nxt.pn * tstep : cB;
;         for (int t = 0; t < nt; t += 2) {
;             const bool last = (t == nt - 2);
;             const char* a1 = cA + (size_t)(t + 1) * kstep;
;             const char* a2 = last ? nA : cA + (size_t)(t + 2) * kstep; const char* b2 = last ? nB : cB + (size_t)(t + 2) * kstep;
;     ...
;         for (int a = 0; a < 2; ++a)
; #pragma unroll
;             for (int b = 0; b < 2; ++b)
; #pragma unroll
;                 for (int m = 0; m < 4; ++m)
; #pragma unroll
;                     for (int n = 0; n < 2; ++n) acc[a][b][m][n] = (f32x4){0.f, 0.f, 0.f, 0.f};
.LBB0_215:
	s_ashr_i32 s41, s40, 31
	s_lshl_b64 s[2:3], s[40:41], 19
	v_readlane_b32 s10, v236, 26
	v_readlane_b32 s11, v236, 27
	s_add_u32 s64, s10, s2
	s_addc_u32 s65, s11, s3
	s_and_b64 s[2:3], s[0:1], exec
	s_cselect_b32 s2, s65, s7
	s_cselect_b32 s3, s64, s6
	s_ashr_i32 s63, s62, 31
	s_lshl_b64 s[10:11], s[62:63], 19
	s_add_u32 s66, s68, s10
	s_addc_u32 s67, s69, s11
	s_and_b64 s[10:11], s[0:1], exec
	s_cselect_b32 s5, s67, s9
	s_cselect_b32 s12, s66, s8
	s_add_u32 s6, s6, 0x40080
	s_addc_u32 s7, s7, 0
	s_add_u32 s13, s8, 0x100
	s_addc_u32 s42, s9, 0
	s_mov_b32 s43, -2
	v_mov_b64_e32 v[0:1], 0
	v_mov_b64_e32 v[2:3], 0
	v_mov_b64_e32 v[4:5], 0
	v_mov_b64_e32 v[6:7], 0
	v_mov_b64_e32 v[8:9], 0
	v_mov_b64_e32 v[10:11], 0
	v_mov_b64_e32 v[12:13], 0
	v_mov_b64_e32 v[14:15], 0
	v_mov_b64_e32 v[16:17], 0
	v_mov_b64_e32 v[18:19], 0
	v_mov_b64_e32 v[20:21], 0
	v_mov_b64_e32 v[22:23], 0
	v_mov_b64_e32 v[24:25], 0
	v_mov_b64_e32 v[26:27], 0
	v_mov_b64_e32 v[28:29], 0
	v_mov_b64_e32 v[30:31], 0
	v_mov_b64_e32 v[32:33], 0
	v_mov_b64_e32 v[34:35], 0
	v_mov_b64_e32 v[36:37], 0
	v_mov_b64_e32 v[38:39], 0
	v_mov_b64_e32 v[40:41], 0
	v_mov_b64_e32 v[42:43], 0
	v_mov_b64_e32 v[44:45], 0
	v_mov_b64_e32 v[46:47], 0
	v_mov_b64_e32 v[48:49], 0
	v_mov_b64_e32 v[50:51], 0
	v_mov_b64_e32 v[52:53], 0
	v_mov_b64_e32 v[54:55], 0
	v_mov_b64_e32 v[56:57], 0
	v_mov_b64_e32 v[58:59], 0
	v_mov_b64_e32 v[60:61], 0
	v_mov_b64_e32 v[62:63], 0
	v_mov_b64_e32 v[64:65], 0
	v_mov_b64_e32 v[66:67], 0
	v_mov_b64_e32 v[68:69], 0
	v_mov_b64_e32 v[70:71], 0
	v_mov_b64_e32 v[72:73], 0
	v_mov_b64_e32 v[74:75], 0
	v_mov_b64_e32 v[76:77], 0
	v_mov_b64_e32 v[78:79], 0
	v_mov_b64_e32 v[80:81], 0
	v_mov_b64_e32 v[82:83], 0
	v_mov_b64_e32 v[84:85], 0
	v_mov_b64_e32 v[86:87], 0
	v_mov_b64_e32 v[88:89], 0
	v_mov_b64_e32 v[90:91], 0
	v_mov_b64_e32 v[92:93], 0
	v_mov_b64_e32 v[94:95], 0
	v_mov_b64_e32 v[96:97], 0
	v_mov_b64_e32 v[98:99], 0
	v_mov_b64_e32 v[100:101], 0
	v_mov_b64_e32 v[102:103], 0
	v_mov_b64_e32 v[104:105], 0
	v_mov_b64_e32 v[106:107], 0
	v_mov_b64_e32 v[108:109], 0
	v_mov_b64_e32 v[110:111], 0
	v_mov_b64_e32 v[112:113], 0
	v_mov_b64_e32 v[114:115], 0
	v_mov_b64_e32 v[116:117], 0
	v_mov_b64_e32 v[118:119], 0
	v_mov_b64_e32 v[120:121], 0
	v_mov_b64_e32 v[122:123], 0
	v_mov_b64_e32 v[124:125], 0
	v_mov_b64_e32 v[126:127], 0

; template <class Epi, class Sched, bool ALIGN_EPI, bool SP2>
; __device__ __forceinline__ void gemm_phase(LAS unsigned char* lds, const Gemm g, const Sched& S, const Epi& E) {
;     ...
;         const char* nA = has_next ? (const char*)(nxt.seg ? g.A1 : g.A0) + (size_t)nxt.pm * tstep : cA; const char* nB = has_next ? (const char*)(nxt.seg ? g.B1 : g.B0) + (size_t)nxt.pn * tstep : cB;
;         for (int t = 0; t < nt; t += 2) {
;             const bool last = (t == nt - 2);
;             const char* a1 = cA + (size_t)(t + 1) * kstep;
;             const char* a2 = last ? nA : cA + (size_t)(t + 2) * kstep; const char* b2 = last ? nB : cB + (size_t)(t + 2) * kstep;
;     ...
;         for (int a = 0; a < 2; ++a)
; #pragma unroll
;             for (int b = 0; b < 2; ++b)
; #pragma unroll
;                 for (int m = 0; m < 4; ++m)
; #pragma unroll
;                     for (int n = 0; n < 2; ++n) acc[a][b][m][n] = (f32x4){0.f, 0.f, 0.f, 0.f};
.LBB0_292:
	s_ashr_i32 s27, s26, 31
	s_lshl_b64 s[28:29], s[26:27], 19
	s_add_u32 s28, s2, s28
	s_addc_u32 s29, s3, s29
	s_and_b64 s[30:31], s[0:1], exec
	s_cselect_b32 s27, s29, s35
	s_cselect_b32 s58, s28, s34
	s_ashr_i32 s25, s24, 31
	s_lshl_b64 s[30:31], s[24:25], 19
	v_readlane_b32 s38, v236, 26
	v_readlane_b32 s39, v236, 27
	s_add_u32 s30, s38, s30
	s_addc_u32 s31, s39, s31
	s_and_b64 s[38:39], s[0:1], exec
	s_cselect_b32 s25, s31, s37
	s_cselect_b32 s59, s30, s36
	s_add_u32 s34, s34, 0x40080
	s_addc_u32 s35, s35, 0
	s_add_u32 s60, s36, 0x100
	s_addc_u32 s61, s37, 0
	s_mov_b32 s62, -2
	v_mov_b64_e32 v[0:1], 0
	v_mov_b64_e32 v[2:3], 0
	v_mov_b64_e32 v[4:5], 0
	v_mov_b64_e32 v[6:7], 0
	v_mov_b64_e32 v[8:9], 0
	v_mov_b64_e32 v[10:11], 0
	v_mov_b64_e32 v[12:13], 0
	v_mov_b64_e32 v[14:15], 0
	v_mov_b64_e32 v[16:17], 0
	v_mov_b64_e32 v[18:19], 0
	v_mov_b64_e32 v[20:21], 0
	v_mov_b64_e32 v[22:23], 0
	v_mov_b64_e32 v[24:25], 0
	v_mov_b64_e32 v[26:27], 0
	v_mov_b64_e32 v[28:29], 0
	v_mov_b64_e32 v[30:31], 0
	v_mov_b64_e32 v[32:33], 0
	v_mov_b64_e32 v[34:35], 0
	v_mov_b64_e32 v[36:37], 0
	v_mov_b64_e32 v[38:39], 0
	v_mov_b64_e32 v[40:41], 0
	v_mov_b64_e32 v[42:43], 0
	v_mov_b64_e32 v[44:45], 0
	v_mov_b64_e32 v[46:47], 0
	v_mov_b64_e32 v[48:49], 0
	v_mov_b64_e32 v[50:51], 0
	v_mov_b64_e32 v[52:53], 0
	v_mov_b64_e32 v[54:55], 0
	v_mov_b64_e32 v[56:57], 0
	v_mov_b64_e32 v[58:59], 0
	v_mov_b64_e32 v[60:61], 0
	v_mov_b64_e32 v[62:63], 0
	v_mov_b64_e32 v[64:65], 0
	v_mov_b64_e32 v[66:67], 0
	v_mov_b64_e32 v[68:69], 0
	v_mov_b64_e32 v[70:71], 0
	v_mov_b64_e32 v[72:73], 0
	v_mov_b64_e32 v[74:75], 0
	v_mov_b64_e32 v[76:77], 0
	v_mov_b64_e32 v[78:79], 0
	v_mov_b64_e32 v[80:81], 0
	v_mov_b64_e32 v[82:83], 0
	v_mov_b64_e32 v[84:85], 0
	v_mov_b64_e32 v[86:87], 0
	v_mov_b64_e32 v[88:89], 0
	v_mov_b64_e32 v[90:91], 0
	v_mov_b64_e32 v[92:93], 0
	v_mov_b64_e32 v[94:95], 0
	v_mov_b64_e32 v[96:97], 0
	v_mov_b64_e32 v[98:99], 0
	v_mov_b64_e32 v[100:101], 0
	v_mov_b64_e32 v[102:103], 0
	v_mov_b64_e32 v[104:105], 0
	v_mov_b64_e32 v[106:107], 0
	v_mov_b64_e32 v[108:109], 0
	v_mov_b64_e32 v[110:111], 0
	v_mov_b64_e32 v[112:113], 0
	v_mov_b64_e32 v[114:115], 0
	v_mov_b64_e32 v[116:117], 0
	v_mov_b64_e32 v[118:119], 0
	v_mov_b64_e32 v[120:121], 0
	v_mov_b64_e32 v[122:123], 0
	v_mov_b64_e32 v[124:125], 0
	v_mov_b64_e32 v[126:127], 0

; template <class Epi, class Sched, bool ALIGN_EPI, bool SP2>
; __device__ __forceinline__ void gemm_phase(LAS unsigned char* lds, const Gemm g, const Sched& S, const Epi& E) {
;     ...
;         const char* nA = has_next ? (const char*)(nxt.seg ? g.A1 : g.A0) + (size_t)nxt.pm * tstep : cA; const char* nB = has_next ? (const char*)(nxt.seg ? g.B1 : g.B0) + (size_t)nxt.pn * tstep : cB;
;         for (int t = 0; t < nt; t += 2) {
;             const bool last = (t == nt - 2);
;             const char* a1 = cA + (size_t)(t + 1) * kstep;
;             const char* a2 = last ? nA : cA + (size_t)(t + 2) * kstep; const char* b2 = last ? nB : cB + (size_t)(t + 2) * kstep;
;     ...
;         for (int a = 0; a < 2; ++a)
; #pragma unroll
;             for (int b = 0; b < 2; ++b)
; #pragma unroll
;                 for (int m = 0; m < 4; ++m)
; #pragma unroll
;                     for (int n = 0; n < 2; ++n) acc[a][b][m][n] = (f32x4){0.f, 0.f, 0.f, 0.f};
.LBB0_552:
	s_ashr_i32 s23, s22, 31
	s_lshl_b64 s[26:27], s[22:23], 19
	s_add_u32 s26, s3, s26
	s_addc_u32 s27, s33, s27
	s_and_b64 s[28:29], s[0:1], exec
	s_cselect_b32 s23, s27, s35
	s_cselect_b32 s51, s26, s34
	s_ashr_i32 s25, s24, 31
	s_lshl_b64 s[28:29], s[24:25], 19
	s_add_u32 s28, s71, s28
	s_addc_u32 s29, s72, s29
	s_and_b64 s[38:39], s[0:1], exec
	s_cselect_b32 s25, s29, s37
	s_cselect_b32 s56, s28, s36
	s_add_u32 s34, s34, 0x40080
	s_addc_u32 s35, s35, 0
	s_add_u32 s57, s36, 0x100
	s_addc_u32 s58, s37, 0
	s_mov_b32 s59, -2
	s_waitcnt vmcnt(0)
	v_mov_b64_e32 v[0:1], 0
	v_mov_b64_e32 v[2:3], 0
	v_mov_b64_e32 v[4:5], 0
	v_mov_b64_e32 v[6:7], 0
	v_mov_b64_e32 v[8:9], 0
	v_mov_b64_e32 v[10:11], 0
	v_mov_b64_e32 v[12:13], 0
	v_mov_b64_e32 v[14:15], 0
	v_mov_b64_e32 v[16:17], 0
	v_mov_b64_e32 v[18:19], 0
	v_mov_b64_e32 v[20:21], 0
	v_mov_b64_e32 v[22:23], 0
	v_mov_b64_e32 v[24:25], 0
	v_mov_b64_e32 v[26:27], 0
	v_mov_b64_e32 v[28:29], 0
	v_mov_b64_e32 v[30:31], 0
	v_mov_b64_e32 v[32:33], 0
	v_mov_b64_e32 v[34:35], 0
	v_mov_b64_e32 v[36:37], 0
	v_mov_b64_e32 v[38:39], 0
	v_mov_b64_e32 v[40:41], 0
	v_mov_b64_e32 v[42:43], 0
	v_mov_b64_e32 v[44:45], 0
	v_mov_b64_e32 v[46:47], 0
	v_mov_b64_e32 v[48:49], 0
	v_mov_b64_e32 v[50:51], 0
	v_mov_b64_e32 v[52:53], 0
	v_mov_b64_e32 v[54:55], 0
	v_mov_b64_e32 v[56:57], 0
	v_mov_b64_e32 v[58:59], 0
	v_mov_b64_e32 v[60:61], 0
	v_mov_b64_e32 v[62:63], 0
	v_mov_b64_e32 v[64:65], 0
	v_mov_b64_e32 v[66:67], 0
	v_mov_b64_e32 v[68:69], 0
	v_mov_b64_e32 v[70:71], 0
	v_mov_b64_e32 v[72:73], 0
	v_mov_b64_e32 v[74:75], 0
	v_mov_b64_e32 v[76:77], 0
	v_mov_b64_e32 v[78:79], 0
	v_mov_b64_e32 v[80:81], 0
	v_mov_b64_e32 v[82:83], 0
	v_mov_b64_e32 v[84:85], 0
	v_mov_b64_e32 v[86:87], 0
	v_mov_b64_e32 v[88:89], 0
	v_mov_b64_e32 v[90:91], 0
	v_mov_b64_e32 v[92:93], 0
	v_mov_b64_e32 v[94:95], 0
	v_mov_b64_e32 v[96:97], 0
	v_mov_b64_e32 v[98:99], 0
	v_mov_b64_e32 v[100:101], 0
	v_mov_b64_e32 v[102:103], 0
	v_mov_b64_e32 v[104:105], 0
	v_mov_b64_e32 v[106:107], 0
	v_mov_b64_e32 v[108:109], 0
	v_mov_b64_e32 v[110:111], 0
	v_mov_b64_e32 v[112:113], 0
	v_mov_b64_e32 v[114:115], 0
	v_mov_b64_e32 v[116:117], 0
	v_mov_b64_e32 v[118:119], 0
	v_mov_b64_e32 v[120:121], 0
	v_mov_b64_e32 v[122:123], 0
	v_mov_b64_e32 v[124:125], 0
	v_mov_b64_e32 v[126:127], 0

; template <class Epi, class Sched, bool ALIGN_EPI, bool SP2>
; __device__ __forceinline__ void gemm_phase(LAS unsigned char* lds, const Gemm g, const Sched& S, const Epi& E) {
;     ...
;         const char* nA = has_next ? (const char*)(nxt.seg ? g.A1 : g.A0) + (size_t)nxt.pm * tstep : cA; const char* nB = has_next ? (const char*)(nxt.seg ? g.B1 : g.B0) + (size_t)nxt.pn * tstep : cB;
;         for (int t = 0; t < nt; t += 2) {
;             const bool last = (t == nt - 2);
;             const char* a1 = cA + (size_t)(t + 1) * kstep;
;             const char* a2 = last ? nA : cA + (size_t)(t + 2) * kstep; const char* b2 = last ? nB : cB + (size_t)(t + 2) * kstep;
;     ...
;         for (int a = 0; a < 2; ++a)
; #pragma unroll
;             for (int b = 0; b < 2; ++b)
; #pragma unroll
;                 for (int m = 0; m < 4; ++m)
; #pragma unroll
;                     for (int n = 0; n < 2; ++n) acc[a][b][m][n] = (f32x4){0.f, 0.f, 0.f, 0.f};
.LBB0_682:
	s_ashr_i32 s15, s14, 31
	s_lshl_b64 s[18:19], s[14:15], 19
	v_readlane_b32 s20, v236, 26
	v_readlane_b32 s21, v236, 27
	s_add_u32 s18, s20, s18
	s_addc_u32 s19, s21, s19
	s_and_b64 s[20:21], s[0:1], exec
	s_cselect_b32 s15, s19, s25
	s_cselect_b32 s48, s18, s24
	s_ashr_i32 s17, s16, 31
	s_lshl_b64 s[20:21], s[16:17], 19
	s_add_u32 s20, s2, s20
	s_addc_u32 s21, s3, s21
	s_and_b64 s[28:29], s[0:1], exec
	s_cselect_b32 s17, s21, s27
	s_cselect_b32 s49, s20, s26
	s_add_u32 s24, s24, 0x40080
	s_addc_u32 s25, s25, 0
	s_add_u32 s50, s26, 0x100
	s_addc_u32 s51, s27, 0
	s_mov_b32 s52, -2
	v_mov_b64_e32 v[0:1], 0
	v_mov_b64_e32 v[2:3], 0
	v_mov_b64_e32 v[4:5], 0
	v_mov_b64_e32 v[6:7], 0
	v_mov_b64_e32 v[8:9], 0
	v_mov_b64_e32 v[10:11], 0
	v_mov_b64_e32 v[12:13], 0
	v_mov_b64_e32 v[14:15], 0
	v_mov_b64_e32 v[16:17], 0
	v_mov_b64_e32 v[18:19], 0
	v_mov_b64_e32 v[20:21], 0
	v_mov_b64_e32 v[22:23], 0
	v_mov_b64_e32 v[24:25], 0
	v_mov_b64_e32 v[26:27], 0
	v_mov_b64_e32 v[28:29], 0
	v_mov_b64_e32 v[30:31], 0
	v_mov_b64_e32 v[32:33], 0
	v_mov_b64_e32 v[34:35], 0
	v_mov_b64_e32 v[36:37], 0
	v_mov_b64_e32 v[38:39], 0
	v_mov_b64_e32 v[40:41], 0
	v_mov_b64_e32 v[42:43], 0
	v_mov_b64_e32 v[44:45], 0
	v_mov_b64_e32 v[46:47], 0
	v_mov_b64_e32 v[48:49], 0
	v_mov_b64_e32 v[50:51], 0
	v_mov_b64_e32 v[52:53], 0
	v_mov_b64_e32 v[54:55], 0
	v_mov_b64_e32 v[56:57], 0
	v_mov_b64_e32 v[58:59], 0
	v_mov_b64_e32 v[60:61], 0
	v_mov_b64_e32 v[62:63], 0
	v_mov_b64_e32 v[64:65], 0
	v_mov_b64_e32 v[66:67], 0
	v_mov_b64_e32 v[68:69], 0
	v_mov_b64_e32 v[70:71], 0
	v_mov_b64_e32 v[72:73], 0
	v_mov_b64_e32 v[74:75], 0
	v_mov_b64_e32 v[76:77], 0
	v_mov_b64_e32 v[78:79], 0
	v_mov_b64_e32 v[80:81], 0
	v_mov_b64_e32 v[82:83], 0
	v_mov_b64_e32 v[84:85], 0
	v_mov_b64_e32 v[86:87], 0
	v_mov_b64_e32 v[88:89], 0
	v_mov_b64_e32 v[90:91], 0
	v_mov_b64_e32 v[92:93], 0
	v_mov_b64_e32 v[94:95], 0
	v_mov_b64_e32 v[96:97], 0
	v_mov_b64_e32 v[98:99], 0
	v_mov_b64_e32 v[100:101], 0
	v_mov_b64_e32 v[102:103], 0
	v_mov_b64_e32 v[104:105], 0
	v_mov_b64_e32 v[106:107], 0
	v_mov_b64_e32 v[108:109], 0
	v_mov_b64_e32 v[110:111], 0
	v_mov_b64_e32 v[112:113], 0
	v_mov_b64_e32 v[114:115], 0
	v_mov_b64_e32 v[116:117], 0
	v_mov_b64_e32 v[118:119], 0
	v_mov_b64_e32 v[120:121], 0
	v_mov_b64_e32 v[122:123], 0
	v_mov_b64_e32 v[124:125], 0
	v_mov_b64_e32 v[126:127], 0

; template <class Epi, class Sched, bool ALIGN_EPI, bool SP2>
; __device__ __forceinline__ void gemm_phase(LAS unsigned char* lds, const Gemm g, const Sched& S, const Epi& E) {
;     ...
;         for (int a = 0; a < 2; ++a)
; #pragma unroll
;             for (int b = 0; b < 2; ++b)
; #pragma unroll
;                 for (int m = 0; m < 4; ++m)
; #pragma unroll
;                     for (int n = 0; n < 2; ++n) acc[a][b][m][n] = (f32x4){0.f, 0.f, 0.f, 0.f};
.LBB0_765:
	s_add_u32 s54, s26, 0x100
	s_addc_u32 s55, s27, 0
	s_mov_b32 s56, -2
	s_waitcnt vmcnt(0)
	v_mov_b64_e32 v[0:1], 0
	v_mov_b64_e32 v[2:3], 0
	v_mov_b64_e32 v[4:5], 0
	v_mov_b64_e32 v[6:7], 0
	v_mov_b64_e32 v[8:9], 0
	v_mov_b64_e32 v[10:11], 0
	v_mov_b64_e32 v[12:13], 0
	v_mov_b64_e32 v[14:15], 0
	v_mov_b64_e32 v[16:17], 0
	v_mov_b64_e32 v[18:19], 0
	v_mov_b64_e32 v[20:21], 0
	v_mov_b64_e32 v[22:23], 0
	v_mov_b64_e32 v[24:25], 0
	v_mov_b64_e32 v[26:27], 0
	v_mov_b64_e32 v[28:29], 0
	v_mov_b64_e32 v[30:31], 0
	v_mov_b64_e32 v[32:33], 0
	v_mov_b64_e32 v[34:35], 0
	v_mov_b64_e32 v[36:37], 0
	v_mov_b64_e32 v[38:39], 0
	v_mov_b64_e32 v[40:41], 0
	v_mov_b64_e32 v[42:43], 0
	v_mov_b64_e32 v[44:45], 0
	v_mov_b64_e32 v[46:47], 0
	v_mov_b64_e32 v[48:49], 0
	v_mov_b64_e32 v[50:51], 0
	v_mov_b64_e32 v[52:53], 0
	v_mov_b64_e32 v[54:55], 0
	v_mov_b64_e32 v[56:57], 0
	v_mov_b64_e32 v[58:59], 0
	v_mov_b64_e32 v[60:61], 0
	v_mov_b64_e32 v[62:63], 0
	v_mov_b64_e32 v[64:65], 0
	v_mov_b64_e32 v[66:67], 0
	v_mov_b64_e32 v[68:69], 0
	v_mov_b64_e32 v[70:71], 0
	v_mov_b64_e32 v[72:73], 0
	v_mov_b64_e32 v[74:75], 0
	v_mov_b64_e32 v[76:77], 0
	v_mov_b64_e32 v[78:79], 0
	v_mov_b64_e32 v[80:81], 0
	v_mov_b64_e32 v[82:83], 0
	v_mov_b64_e32 v[84:85], 0
	v_mov_b64_e32 v[86:87], 0
	v_mov_b64_e32 v[88:89], 0
	v_mov_b64_e32 v[90:91], 0
	v_mov_b64_e32 v[92:93], 0
	v_mov_b64_e32 v[94:95], 0
	v_mov_b64_e32 v[96:97], 0
	v_mov_b64_e32 v[98:99], 0
	v_mov_b64_e32 v[100:101], 0
	v_mov_b64_e32 v[102:103], 0
	v_mov_b64_e32 v[104:105], 0
	v_mov_b64_e32 v[106:107], 0
	v_mov_b64_e32 v[108:109], 0
	v_mov_b64_e32 v[110:111], 0
	v_mov_b64_e32 v[112:113], 0
	v_mov_b64_e32 v[114:115], 0
	v_mov_b64_e32 v[116:117], 0
	v_mov_b64_e32 v[118:119], 0
	v_mov_b64_e32 v[128:129], 0
	v_mov_b64_e32 v[130:131], 0
	v_mov_b64_e32 v[132:133], 0
	v_mov_b64_e32 v[134:135], 0
